# LN1/LN2 wave reductions via DPP row ops + permlane16/32 swaps instead of 6-hop ds_bpermute
# speedup vs baseline: 1.0023x; 1.0023x over previous
; DI float bflo(unsigned u) { return __uint_as_float(u << 16); }
; DI float bfhi(unsigned u) { return __uint_as_float(u & 0xffff0000u); }
; DI uint4 pk8(f32x4 a, f32x4 b) { return make_uint4(pack2(a[0], a[1]), pack2(a[2], a[3]), pack2(b[0], b[1]), pack2(b[2], b[3])); }
; template <bool TO_BF16>
; DI void phase_ln(const Params& P, const float* gam, const float* bet) {
;     ...
;   for (long row = (long)blockIdx.x * 8 + wid; row < MTOK; row += (long)gridDim.x * 8) {
;     const u16* src = SRC + row * 1024;
;     float v[16];
;     float s = 0.f;
;     for (int k = 0; k < 2; ++k) {
;       const u32x4_ u_ = __builtin_nontemporal_load((const u32x4_*)(src + k * 512 + lane * 8));
;       const uint4 u = make_uint4(u_[0], u_[1], u_[2], u_[3]);
;       v[8 * k + 0] = bflo(u.x); v[8 * k + 1] = bfhi(u.x); v[8 * k + 2] = bflo(u.y); v[8 * k + 3] = bfhi(u.y);
;       v[8 * k + 4] = bflo(u.z); v[8 * k + 5] = bfhi(u.z); v[8 * k + 6] = bflo(u.w); v[8 * k + 7] = bfhi(u.w);
;     }
;     for (int e = 0; e < 16; ++e) s += v[e];
;     for (int d = 1; d < 64; d <<= 1) s += __shfl_xor(s, d);
;     const float mean = s * (1.0f / 1024.0f);
;     float s2 = 0.f;
;     for (int e = 0; e < 16; ++e) { const float d = v[e] - mean; s2 += d * d; }
;     for (int d = 1; d < 64; d <<= 1) s2 += __shfl_xor(s2, d);
;     const float rstd = rsqrtf(s2 * (1.0f / 1024.0f) + 1e-5f);
;     for (int k = 0; k < 2; ++k) {
;       const int c = k * 512 + lane * 8;
;       f32x4 g0 = *(const f32x4*)(gam + c), g1 = *(const f32x4*)(gam + c + 4), b0 = *(const f32x4*)(bet + c), b1 = *(const f32x4*)(bet + c + 4), r0, r1;
;       for (int j = 0; j < 4; ++j) { r0[j] = (v[8 * k + j] - mean) * rstd * g0[j] + b0[j]; r1[j] = (v[8 * k + 4 + j] - mean) * rstd * g1[j] + b1[j]; }
;       if (TO_BF16) *(uint4*)(X1 + row * 1024 + c) = pk8(r0, r1);
;       else { __builtin_nontemporal_store(r0, (f32x4*)(Y + row * 1024 + c)); __builtin_nontemporal_store(r1, (f32x4*)(Y + row * 1024 + c + 4)); }
;     }
.LBB0_930:
	s_waitcnt vmcnt(2)
	v_lshlrev_b32_e32 v40, 16, v18
	v_and_b32_e32 v41, 0xffff0000, v18
	v_lshlrev_b32_e32 v36, 16, v19
	v_and_b32_e32 v37, 0xffff0000, v19
	v_lshlrev_b32_e32 v38, 16, v20
	v_and_b32_e32 v39, 0xffff0000, v20
	v_lshlrev_b32_e32 v34, 16, v21
	v_and_b32_e32 v35, 0xffff0000, v21
	v_lshlrev_b32_e32 v48, 16, v22
	v_and_b32_e32 v49, 0xffff0000, v22
	v_lshlrev_b32_e32 v44, 16, v23
	v_and_b32_e32 v45, 0xffff0000, v23
	v_lshlrev_b32_e32 v46, 16, v24
	v_and_b32_e32 v47, 0xffff0000, v24
	v_lshlrev_b32_e32 v42, 16, v25
	v_and_b32_e32 v43, 0xffff0000, v25
	v_lshl_add_u64 v[2:3], v[2:3], 0, s[2:3]
	v_lshl_add_u64 v[70:71], v[70:71], 0, s[4:5]
	s_nop 0
	global_load_dwordx4 v[18:21], v[70:71], off nt
	global_load_dwordx4 v[22:25], v[70:71], off offset:1024 nt
	v_add_f32_e32 v26, 0, v40
	v_add_f32_e32 v26, v26, v41
	v_add_f32_e32 v26, v26, v36
	v_add_f32_e32 v26, v26, v37
	v_add_f32_e32 v26, v26, v38
	v_add_f32_e32 v26, v26, v39
	v_add_f32_e32 v26, v26, v34
	v_add_f32_e32 v26, v26, v35
	v_add_f32_e32 v26, v26, v48
	v_add_f32_e32 v26, v26, v49
	v_add_f32_e32 v26, v26, v44
	v_add_f32_e32 v26, v26, v45
	v_add_f32_e32 v26, v26, v46
	v_add_f32_e32 v26, v26, v47
	v_add_f32_e32 v26, v26, v42
	v_add_f32_e32 v26, v26, v43
	s_nop 1
	v_add_f32_dpp v27, v26, v26 quad_perm:[1,0,3,2] row_mask:0xf bank_mask:0xf
	s_nop 1
	v_add_f32_dpp v26, v27, v27 quad_perm:[2,3,0,1] row_mask:0xf bank_mask:0xf
	s_nop 1
	v_add_f32_dpp v27, v26, v26 row_half_mirror row_mask:0xf bank_mask:0xf
	s_nop 1
	v_add_f32_dpp v26, v27, v27 row_mirror row_mask:0xf bank_mask:0xf
	v_mov_b32_e32 v27, v26
	s_nop 1
	v_permlane16_swap_b32_e32 v26, v27
	s_nop 1
	v_add_f32_e32 v26, v26, v27
	v_mov_b32_e32 v27, v26
	s_nop 1
	v_permlane32_swap_b32_e32 v26, v27
	s_nop 1
	v_add_f32_e32 v26, v26, v27
	v_mul_f32_e32 v50, 0x3a800000, v26
	v_pk_add_f32 v[40:41], v[40:41], v[50:51] op_sel_hi:[1,0] neg_lo:[0,1] neg_hi:[0,1]
	v_pk_add_f32 v[36:37], v[36:37], v[50:51] op_sel_hi:[1,0] neg_lo:[0,1] neg_hi:[0,1]
	v_pk_add_f32 v[38:39], v[38:39], v[50:51] op_sel_hi:[1,0] neg_lo:[0,1] neg_hi:[0,1]
	v_pk_add_f32 v[34:35], v[34:35], v[50:51] op_sel_hi:[1,0] neg_lo:[0,1] neg_hi:[0,1]
	v_pk_add_f32 v[48:49], v[48:49], v[50:51] op_sel_hi:[1,0] neg_lo:[0,1] neg_hi:[0,1]
	v_pk_add_f32 v[44:45], v[44:45], v[50:51] op_sel_hi:[1,0] neg_lo:[0,1] neg_hi:[0,1]
	v_pk_add_f32 v[46:47], v[46:47], v[50:51] op_sel_hi:[1,0] neg_lo:[0,1] neg_hi:[0,1]
	v_pk_add_f32 v[42:43], v[42:43], v[50:51] op_sel_hi:[1,0] neg_lo:[0,1] neg_hi:[0,1]
	v_pk_mul_f32 v[50:51], v[40:41], v[40:41]
	v_pk_mul_f32 v[52:53], v[36:37], v[36:37]
	v_add_f32_e32 v50, v50, v51
	v_add_f32_e32 v50, v52, v50
	v_pk_mul_f32 v[54:55], v[38:39], v[38:39]
	v_add_f32_e32 v50, v53, v50
	v_add_f32_e32 v50, v54, v50
	v_pk_mul_f32 v[56:57], v[34:35], v[34:35]
	v_add_f32_e32 v50, v55, v50
	v_add_f32_e32 v50, v56, v50
	v_pk_mul_f32 v[58:59], v[48:49], v[48:49]
	v_add_f32_e32 v50, v57, v50
	v_add_f32_e32 v50, v58, v50
	v_pk_mul_f32 v[60:61], v[44:45], v[44:45]
	v_add_f32_e32 v50, v59, v50
	v_add_f32_e32 v50, v60, v50
	v_pk_mul_f32 v[62:63], v[46:47], v[46:47]
	v_add_f32_e32 v50, v61, v50
	v_add_f32_e32 v50, v62, v50
	v_pk_mul_f32 v[64:65], v[42:43], v[42:43]
	v_add_f32_e32 v50, v63, v50
	v_add_f32_e32 v50, v64, v50
	v_add_f32_e32 v50, v65, v50
	s_nop 1
	v_add_f32_dpp v51, v50, v50 quad_perm:[1,0,3,2] row_mask:0xf bank_mask:0xf
	s_nop 1
	v_add_f32_dpp v50, v51, v51 quad_perm:[2,3,0,1] row_mask:0xf bank_mask:0xf
	s_nop 1
	v_add_f32_dpp v51, v50, v50 row_half_mirror row_mask:0xf bank_mask:0xf
	s_nop 1
	v_add_f32_dpp v50, v51, v51 row_mirror row_mask:0xf bank_mask:0xf
	v_mov_b32_e32 v51, v50
	s_nop 1
	v_permlane16_swap_b32_e32 v50, v51
	s_nop 1
	v_add_f32_e32 v50, v50, v51
	v_mov_b32_e32 v51, v50
	s_nop 1
	v_permlane32_swap_b32_e32 v50, v51
	s_nop 1
	v_add_f32_e32 v50, v50, v51
	v_fmamk_f32 v50, v50, 0x3a800000, v17
	v_mul_f32_e32 v51, 0x4b800000, v50
	v_cmp_gt_f32_e32 vcc, s10, v50
	s_nop 1
	v_cndmask_b32_e32 v50, v50, v51, vcc
	v_rsq_f32_e32 v50, v50
	s_nop 0
	v_mul_f32_e32 v51, 0x45800000, v50
	v_cndmask_b32_e32 v50, v50, v51, vcc
	v_pk_mul_f32 v[40:41], v[40:41], v[50:51] op_sel_hi:[1,0]
	v_pk_mul_f32 v[38:39], v[38:39], v[50:51] op_sel_hi:[1,0]
	v_pk_mul_f32 v[36:37], v[36:37], v[50:51] op_sel_hi:[1,0]
	v_pk_mul_f32 v[34:35], v[34:35], v[50:51] op_sel_hi:[1,0]
	v_pk_fma_f32 v[26:27], v[74:75], v[40:41], v[82:83]
	v_pk_fma_f32 v[30:31], v[78:79], v[38:39], v[86:87]
	v_pk_fma_f32 v[28:29], v[76:77], v[36:37], v[84:85]
	v_pk_fma_f32 v[32:33], v[80:81], v[34:35], v[88:89]
	v_cvt_pk_bf16_f32 v26, v26, v27
	v_cvt_pk_bf16_f32 v27, v28, v29
	v_cvt_pk_bf16_f32 v28, v30, v31
	v_cvt_pk_bf16_f32 v29, v32, v33
	global_store_dwordx4 v[8:9], v[26:29], off
	v_pk_mul_f32 v[34:35], v[48:49], v[50:51] op_sel_hi:[1,0]
	v_pk_mul_f32 v[36:37], v[46:47], v[50:51] op_sel_hi:[1,0]
	v_pk_mul_f32 v[38:39], v[44:45], v[50:51] op_sel_hi:[1,0]
	v_pk_mul_f32 v[40:41], v[42:43], v[50:51] op_sel_hi:[1,0]
	v_cmp_lt_u64_e32 vcc, s[8:9], v[2:3]
	s_or_b64 s[6:7], vcc, s[6:7]
	v_pk_fma_f32 v[52:53], v[90:91], v[34:35], v[98:99]
	v_pk_fma_f32 v[56:57], v[94:95], v[36:37], v[102:103]
	v_pk_fma_f32 v[54:55], v[92:93], v[38:39], v[100:101]
	v_pk_fma_f32 v[58:59], v[96:97], v[40:41], v[104:105]
	v_cvt_pk_bf16_f32 v30, v52, v53
	v_cvt_pk_bf16_f32 v31, v54, v55
	v_cvt_pk_bf16_f32 v32, v56, v57
	v_cvt_pk_bf16_f32 v33, v58, v59
	global_store_dwordx4 v[8:9], v[30:33], off offset:1024
	v_lshl_add_u64 v[8:9], v[8:9], 0, s[4:5]
	s_andn2_b64 exec, exec, s[6:7]
	s_cbranch_execnz .LBB0_930
	s_waitcnt vmcnt(0)

; DI float bflo(unsigned u) { return __uint_as_float(u << 16); }
; DI float bfhi(unsigned u) { return __uint_as_float(u & 0xffff0000u); }
; DI uint4 pk8(f32x4 a, f32x4 b) { return make_uint4(pack2(a[0], a[1]), pack2(a[2], a[3]), pack2(b[0], b[1]), pack2(b[2], b[3])); }
; template <bool TO_BF16>
; DI void phase_ln(const Params& P, const float* gam, const float* bet) {
;     ...
;   for (long row = (long)blockIdx.x * 8 + wid; row < MTOK; row += (long)gridDim.x * 8) {
;     const u16* src = SRC + row * 1024;
;     float v[16];
;     float s = 0.f;
;     for (int k = 0; k < 2; ++k) {
;       const u32x4_ u_ = __builtin_nontemporal_load((const u32x4_*)(src + k * 512 + lane * 8));
;       const uint4 u = make_uint4(u_[0], u_[1], u_[2], u_[3]);
;       v[8 * k + 0] = bflo(u.x); v[8 * k + 1] = bfhi(u.x); v[8 * k + 2] = bflo(u.y); v[8 * k + 3] = bfhi(u.y);
;       v[8 * k + 4] = bflo(u.z); v[8 * k + 5] = bfhi(u.z); v[8 * k + 6] = bflo(u.w); v[8 * k + 7] = bfhi(u.w);
;     }
;     for (int e = 0; e < 16; ++e) s += v[e];
;     for (int d = 1; d < 64; d <<= 1) s += __shfl_xor(s, d);
;     const float mean = s * (1.0f / 1024.0f);
;     float s2 = 0.f;
;     for (int e = 0; e < 16; ++e) { const float d = v[e] - mean; s2 += d * d; }
;     for (int d = 1; d < 64; d <<= 1) s2 += __shfl_xor(s2, d);
;     const float rstd = rsqrtf(s2 * (1.0f / 1024.0f) + 1e-5f);
;     for (int k = 0; k < 2; ++k) {
;       const int c = k * 512 + lane * 8;
;       f32x4 g0 = *(const f32x4*)(gam + c), g1 = *(const f32x4*)(gam + c + 4), b0 = *(const f32x4*)(bet + c), b1 = *(const f32x4*)(bet + c + 4), r0, r1;
;       for (int j = 0; j < 4; ++j) { r0[j] = (v[8 * k + j] - mean) * rstd * g0[j] + b0[j]; r1[j] = (v[8 * k + 4 + j] - mean) * rstd * g1[j] + b1[j]; }
;       if (TO_BF16) *(uint4*)(X1 + row * 1024 + c) = pk8(r0, r1);
;       else { __builtin_nontemporal_store(r0, (f32x4*)(Y + row * 1024 + c)); __builtin_nontemporal_store(r1, (f32x4*)(Y + row * 1024 + c + 4)); }
;     }
.LBB0_998:
	s_waitcnt vmcnt(4)
	v_lshlrev_b32_e32 v46, 16, v20
	v_and_b32_e32 v47, 0xffff0000, v20
	v_lshlrev_b32_e32 v28, 16, v21
	v_and_b32_e32 v29, 0xffff0000, v21
	v_lshlrev_b32_e32 v44, 16, v22
	v_and_b32_e32 v45, 0xffff0000, v22
	v_lshlrev_b32_e32 v30, 16, v23
	v_and_b32_e32 v31, 0xffff0000, v23
	v_lshlrev_b32_e32 v50, 16, v24
	v_and_b32_e32 v51, 0xffff0000, v24
	v_lshlrev_b32_e32 v32, 16, v25
	v_and_b32_e32 v33, 0xffff0000, v25
	v_lshlrev_b32_e32 v48, 16, v26
	v_and_b32_e32 v49, 0xffff0000, v26
	v_lshlrev_b32_e32 v34, 16, v27
	v_and_b32_e32 v35, 0xffff0000, v27
	v_lshl_add_u64 v[2:3], v[2:3], 0, s[2:3]
	global_load_dwordx4 v[20:23], v[10:11], off nt
	global_load_dwordx4 v[24:27], v[10:11], off offset:1024 nt
	v_lshl_add_u64 v[10:11], v[10:11], 0, s[6:7]
	v_add_f32_e32 v19, 0, v46
	v_add_f32_e32 v19, v19, v47
	v_add_f32_e32 v19, v19, v28
	v_add_f32_e32 v19, v19, v29
	v_add_f32_e32 v19, v19, v44
	v_add_f32_e32 v19, v19, v45
	v_add_f32_e32 v19, v19, v30
	v_add_f32_e32 v19, v19, v31
	v_add_f32_e32 v19, v19, v50
	v_add_f32_e32 v19, v19, v51
	v_add_f32_e32 v19, v19, v32
	v_add_f32_e32 v19, v19, v33
	v_add_f32_e32 v19, v19, v48
	v_add_f32_e32 v19, v19, v49
	v_add_f32_e32 v19, v19, v34
	v_add_f32_e32 v19, v19, v35
	s_nop 1
	v_add_f32_dpp v52, v19, v19 quad_perm:[1,0,3,2] row_mask:0xf bank_mask:0xf
	s_nop 1
	v_add_f32_dpp v19, v52, v52 quad_perm:[2,3,0,1] row_mask:0xf bank_mask:0xf
	s_nop 1
	v_add_f32_dpp v52, v19, v19 row_half_mirror row_mask:0xf bank_mask:0xf
	s_nop 1
	v_add_f32_dpp v19, v52, v52 row_mirror row_mask:0xf bank_mask:0xf
	v_mov_b32_e32 v52, v19
	s_nop 1
	v_permlane16_swap_b32_e32 v19, v52
	s_nop 1
	v_add_f32_e32 v19, v19, v52
	v_mov_b32_e32 v52, v19
	s_nop 1
	v_permlane32_swap_b32_e32 v19, v52
	s_nop 1
	v_add_f32_e32 v19, v19, v52
	v_mul_f32_e32 v52, 0x3a800000, v19
	v_pk_add_f32 v[46:47], v[46:47], v[52:53] op_sel_hi:[1,0] neg_lo:[0,1] neg_hi:[0,1]
	v_pk_add_f32 v[28:29], v[28:29], v[52:53] op_sel_hi:[1,0] neg_lo:[0,1] neg_hi:[0,1]
	v_pk_add_f32 v[44:45], v[44:45], v[52:53] op_sel_hi:[1,0] neg_lo:[0,1] neg_hi:[0,1]
	v_pk_add_f32 v[30:31], v[30:31], v[52:53] op_sel_hi:[1,0] neg_lo:[0,1] neg_hi:[0,1]
	v_pk_add_f32 v[50:51], v[50:51], v[52:53] op_sel_hi:[1,0] neg_lo:[0,1] neg_hi:[0,1]
	v_pk_add_f32 v[32:33], v[32:33], v[52:53] op_sel_hi:[1,0] neg_lo:[0,1] neg_hi:[0,1]
	v_pk_add_f32 v[48:49], v[48:49], v[52:53] op_sel_hi:[1,0] neg_lo:[0,1] neg_hi:[0,1]
	v_pk_add_f32 v[34:35], v[34:35], v[52:53] op_sel_hi:[1,0] neg_lo:[0,1] neg_hi:[0,1]
	v_pk_mul_f32 v[56:57], v[46:47], v[46:47]
	v_pk_mul_f32 v[58:59], v[28:29], v[28:29]
	v_pk_mul_f32 v[60:61], v[44:45], v[44:45]
	v_pk_mul_f32 v[62:63], v[30:31], v[30:31]
	v_pk_mul_f32 v[64:65], v[50:51], v[50:51]
	v_pk_mul_f32 v[66:67], v[32:33], v[32:33]
	v_pk_mul_f32 v[68:69], v[48:49], v[48:49]
	v_pk_mul_f32 v[70:71], v[34:35], v[34:35]
	v_add_f32_e32 v19, v56, v57
	v_add_f32_e32 v19, v58, v19
	v_add_f32_e32 v19, v59, v19
	v_add_f32_e32 v19, v60, v19
	v_add_f32_e32 v19, v61, v19
	v_add_f32_e32 v19, v62, v19
	v_add_f32_e32 v19, v63, v19
	v_add_f32_e32 v19, v64, v19
	v_add_f32_e32 v19, v65, v19
	v_add_f32_e32 v19, v66, v19
	v_add_f32_e32 v19, v67, v19
	v_add_f32_e32 v19, v68, v19
	v_add_f32_e32 v19, v69, v19
	v_add_f32_e32 v19, v70, v19
	v_add_f32_e32 v19, v71, v19
	s_nop 1
	v_add_f32_dpp v52, v19, v19 quad_perm:[1,0,3,2] row_mask:0xf bank_mask:0xf
	s_nop 1
	v_add_f32_dpp v19, v52, v52 quad_perm:[2,3,0,1] row_mask:0xf bank_mask:0xf
	s_nop 1
	v_add_f32_dpp v52, v19, v19 row_half_mirror row_mask:0xf bank_mask:0xf
	s_nop 1
	v_add_f32_dpp v19, v52, v52 row_mirror row_mask:0xf bank_mask:0xf
	v_mov_b32_e32 v52, v19
	s_nop 1
	v_permlane16_swap_b32_e32 v19, v52
	s_nop 1
	v_add_f32_e32 v19, v19, v52
	v_mov_b32_e32 v52, v19
	s_nop 1
	v_permlane32_swap_b32_e32 v19, v52
	s_nop 1
	v_add_f32_e32 v19, v19, v52
	v_fmamk_f32 v19, v19, 0x3a800000, v1
	v_mul_f32_e32 v52, 0x4b800000, v19
	v_cmp_gt_f32_e32 vcc, s12, v19
	s_nop 1
	v_cndmask_b32_e32 v19, v19, v52, vcc
	v_rsq_f32_e32 v19, v19
	s_nop 0
	v_mul_f32_e32 v52, 0x45800000, v19
	v_cndmask_b32_e32 v56, v19, v52, vcc
	v_pk_mul_f32 v[46:47], v[46:47], v[56:57] op_sel_hi:[1,0]
	v_pk_mul_f32 v[28:29], v[28:29], v[56:57] op_sel_hi:[1,0]
	v_pk_mul_f32 v[44:45], v[44:45], v[56:57] op_sel_hi:[1,0]
	v_pk_mul_f32 v[30:31], v[30:31], v[56:57] op_sel_hi:[1,0]
	v_pk_mul_f32 v[50:51], v[50:51], v[56:57] op_sel_hi:[1,0]
	v_pk_mul_f32 v[32:33], v[32:33], v[56:57] op_sel_hi:[1,0]
	v_pk_mul_f32 v[48:49], v[48:49], v[56:57] op_sel_hi:[1,0]
	v_pk_mul_f32 v[34:35], v[34:35], v[56:57] op_sel_hi:[1,0]
	v_pk_fma_f32 v[36:37], v[74:75], v[46:47], v[82:83]
	v_pk_fma_f32 v[38:39], v[76:77], v[28:29], v[84:85]
	v_pk_fma_f32 v[40:41], v[78:79], v[44:45], v[86:87]
	v_pk_fma_f32 v[42:43], v[80:81], v[30:31], v[88:89]
	global_store_dwordx4 v[8:9], v[36:39], off nt
	global_store_dwordx4 v[8:9], v[40:43], off offset:16 nt
	v_cmp_lt_u64_e32 vcc, s[10:11], v[2:3]
	s_or_b64 s[8:9], vcc, s[8:9]
	v_pk_fma_f32 v[58:59], v[90:91], v[50:51], v[98:99]
	v_pk_fma_f32 v[60:61], v[92:93], v[32:33], v[100:101]
	v_pk_fma_f32 v[62:63], v[94:95], v[48:49], v[102:103]
	v_pk_fma_f32 v[64:65], v[96:97], v[34:35], v[104:105]
	global_store_dwordx4 v[8:9], v[58:61], off offset:2048 nt
	global_store_dwordx4 v[8:9], v[62:65], off offset:2064 nt
	v_lshl_add_u64 v[8:9], v[8:9], 0, s[4:5]
	s_andn2_b64 exec, exec, s[8:9]
	s_cbranch_execnz .LBB0_998
	s_waitcnt vmcnt(0)
